# FFN2-down epilogue: all residual loads issued up-front (batched), on top of v5
# baseline (speedup 1.0000x reference)
.LBB0_1005:
	s_lshl_b32 s14, s46, 8
	s_add_i32 s14, s14, s37
	v_add_u32_e32 v144, s14, v168
	s_lshl_b32 s15, s47, 8
	s_or_b32 s15, s15, s38
	v_lshl_add_u32 v145, v169, 3, s15
	v_lshlrev_b32_e32 v146, 2, v145
	s_ashr_i32 s14, s46, 5
	s_mul_hi_i32 s15, s14, 0x9000
	s_mul_i32 s14, s14, 0x9000
	s_add_u32 s14, s35, s14
	s_addc_u32 s15, s36, s15
	global_load_dwordx4 v[160:163], v146, s[14:15] offset:0
	global_load_dwordx4 v[164:167], v146, s[14:15] offset:16
	global_load_dwordx4 v[174:177], v146, s[14:15] offset:512
	global_load_dwordx4 v[178:181], v146, s[14:15] offset:528
	v_lshlrev_b32_e32 v148, 1, v145
	v_lshl_add_u32 v148, v144, 11, v148
	v_lshl_add_u32 v147, v144, 12, v146
	s_add_u32 s14, s6, 0x0
	s_addc_u32 s15, s7, 0
	global_load_dwordx4 v[182:185], v148, s[14:15] offset:0
	s_add_u32 s14, s6, 0x8000
	s_addc_u32 s15, s7, 0
	global_load_dwordx4 v[186:189], v148, s[14:15] offset:0
	s_add_u32 s14, s6, 0x10000
	s_addc_u32 s15, s7, 0
	global_load_dwordx4 v[190:193], v148, s[14:15] offset:0
	s_add_u32 s14, s6, 0x18000
	s_addc_u32 s15, s7, 0
	global_load_dwordx4 v[194:197], v148, s[14:15] offset:0
	s_add_u32 s14, s6, 0x40000
	s_addc_u32 s15, s7, 0
	global_load_dwordx4 v[198:201], v148, s[14:15] offset:0
	s_add_u32 s14, s6, 0x48000
	s_addc_u32 s15, s7, 0
	global_load_dwordx4 v[202:205], v148, s[14:15] offset:0
	s_add_u32 s14, s6, 0x50000
	s_addc_u32 s15, s7, 0
	global_load_dwordx4 v[206:209], v148, s[14:15] offset:0
	s_add_u32 s14, s6, 0x58000
	s_addc_u32 s15, s7, 0
	global_load_dwordx4 v[210:213], v148, s[14:15] offset:0
	s_waitcnt vmcnt(7)
	v_pk_mul_f32 v[160:161], v[160:161], 0.5 op_sel_hi:[1,0]
	v_pk_mul_f32 v[162:163], v[162:163], 0.5 op_sel_hi:[1,0]
	v_pk_mul_f32 v[164:165], v[164:165], 0.5 op_sel_hi:[1,0]
	v_pk_mul_f32 v[166:167], v[166:167], 0.5 op_sel_hi:[1,0]
	v_lshlrev_b32_e32 v152, 16, v182
	v_and_b32_e32 v153, 0xffff0000, v182
	v_lshlrev_b32_e32 v154, 16, v183
	v_and_b32_e32 v155, 0xffff0000, v183
	v_lshlrev_b32_e32 v156, 16, v184
	v_and_b32_e32 v157, 0xffff0000, v184
	v_lshlrev_b32_e32 v158, 16, v185
	v_and_b32_e32 v159, 0xffff0000, v185
	v_pk_fma_f32 v[124:125], v[124:125], v[160:161], v[152:153]
	v_pk_fma_f32 v[126:127], v[126:127], v[162:163], v[154:155]
	v_pk_fma_f32 v[120:121], v[120:121], v[164:165], v[156:157]
	v_pk_fma_f32 v[122:123], v[122:123], v[166:167], v[158:159]
	s_add_u32 s14, s76, 0x0
	s_addc_u32 s15, s77, 0
	global_store_dwordx4 v147, v[124:127], s[14:15] offset:0
	global_store_dwordx4 v147, v[120:123], s[14:15] offset:16
	s_add_u32 s14, s6, 0x0
	s_addc_u32 s15, s7, 0
	global_load_dwordx4 v[182:185], v148, s[14:15] offset:256
	s_waitcnt vmcnt(9)
	v_lshlrev_b32_e32 v152, 16, v186
	v_and_b32_e32 v153, 0xffff0000, v186
	v_lshlrev_b32_e32 v154, 16, v187
	v_and_b32_e32 v155, 0xffff0000, v187
	v_lshlrev_b32_e32 v156, 16, v188
	v_and_b32_e32 v157, 0xffff0000, v188
	v_lshlrev_b32_e32 v158, 16, v189
	v_and_b32_e32 v159, 0xffff0000, v189
	v_pk_fma_f32 v[116:117], v[116:117], v[160:161], v[152:153]
	v_pk_fma_f32 v[118:119], v[118:119], v[162:163], v[154:155]
	v_pk_fma_f32 v[112:113], v[112:113], v[164:165], v[156:157]
	v_pk_fma_f32 v[114:115], v[114:115], v[166:167], v[158:159]
	s_add_u32 s14, s76, 0x10000
	s_addc_u32 s15, s77, 0
	global_store_dwordx4 v147, v[116:119], s[14:15] offset:0
	global_store_dwordx4 v147, v[112:115], s[14:15] offset:16
	s_add_u32 s14, s6, 0x8000
	s_addc_u32 s15, s7, 0
	global_load_dwordx4 v[186:189], v148, s[14:15] offset:256
	s_waitcnt vmcnt(11)
	v_lshlrev_b32_e32 v152, 16, v190
	v_and_b32_e32 v153, 0xffff0000, v190
	v_lshlrev_b32_e32 v154, 16, v191
	v_and_b32_e32 v155, 0xffff0000, v191
	v_lshlrev_b32_e32 v156, 16, v192
	v_and_b32_e32 v157, 0xffff0000, v192
	v_lshlrev_b32_e32 v158, 16, v193
	v_and_b32_e32 v159, 0xffff0000, v193
	v_pk_fma_f32 v[108:109], v[108:109], v[160:161], v[152:153]
	v_pk_fma_f32 v[110:111], v[110:111], v[162:163], v[154:155]
	v_pk_fma_f32 v[104:105], v[104:105], v[164:165], v[156:157]
	v_pk_fma_f32 v[106:107], v[106:107], v[166:167], v[158:159]
	s_add_u32 s14, s76, 0x20000
	s_addc_u32 s15, s77, 0
	global_store_dwordx4 v147, v[108:111], s[14:15] offset:0
	global_store_dwordx4 v147, v[104:107], s[14:15] offset:16
	s_add_u32 s14, s6, 0x10000
	s_addc_u32 s15, s7, 0
	global_load_dwordx4 v[190:193], v148, s[14:15] offset:256
	s_waitcnt vmcnt(13)
	v_lshlrev_b32_e32 v152, 16, v194
	v_and_b32_e32 v153, 0xffff0000, v194
	v_lshlrev_b32_e32 v154, 16, v195
	v_and_b32_e32 v155, 0xffff0000, v195
	v_lshlrev_b32_e32 v156, 16, v196
	v_and_b32_e32 v157, 0xffff0000, v196
	v_lshlrev_b32_e32 v158, 16, v197
	v_and_b32_e32 v159, 0xffff0000, v197
	v_pk_fma_f32 v[100:101], v[100:101], v[160:161], v[152:153]
	v_pk_fma_f32 v[102:103], v[102:103], v[162:163], v[154:155]
	v_pk_fma_f32 v[96:97], v[96:97], v[164:165], v[156:157]
	v_pk_fma_f32 v[98:99], v[98:99], v[166:167], v[158:159]
	s_add_u32 s14, s76, 0x30000
	s_addc_u32 s15, s77, 0
	global_store_dwordx4 v147, v[100:103], s[14:15] offset:0
	global_store_dwordx4 v147, v[96:99], s[14:15] offset:16
	s_add_u32 s14, s6, 0x18000
	s_addc_u32 s15, s7, 0
	global_load_dwordx4 v[194:197], v148, s[14:15] offset:256
	s_waitcnt vmcnt(15)
	v_lshlrev_b32_e32 v152, 16, v198
	v_and_b32_e32 v153, 0xffff0000, v198
	v_lshlrev_b32_e32 v154, 16, v199
	v_and_b32_e32 v155, 0xffff0000, v199
	v_lshlrev_b32_e32 v156, 16, v200
	v_and_b32_e32 v157, 0xffff0000, v200
	v_lshlrev_b32_e32 v158, 16, v201
	v_and_b32_e32 v159, 0xffff0000, v201
	v_pk_fma_f32 v[92:93], v[92:93], v[160:161], v[152:153]
	v_pk_fma_f32 v[94:95], v[94:95], v[162:163], v[154:155]
	v_pk_fma_f32 v[88:89], v[88:89], v[164:165], v[156:157]
	v_pk_fma_f32 v[90:91], v[90:91], v[166:167], v[158:159]
	s_add_u32 s14, s76, 0x80000
	s_addc_u32 s15, s77, 0
	global_store_dwordx4 v147, v[92:95], s[14:15] offset:0
	global_store_dwordx4 v147, v[88:91], s[14:15] offset:16
	s_add_u32 s14, s6, 0x40000
	s_addc_u32 s15, s7, 0
	global_load_dwordx4 v[198:201], v148, s[14:15] offset:256
	s_waitcnt vmcnt(17)
	v_lshlrev_b32_e32 v152, 16, v202
	v_and_b32_e32 v153, 0xffff0000, v202
	v_lshlrev_b32_e32 v154, 16, v203
	v_and_b32_e32 v155, 0xffff0000, v203
	v_lshlrev_b32_e32 v156, 16, v204
	v_and_b32_e32 v157, 0xffff0000, v204
	v_lshlrev_b32_e32 v158, 16, v205
	v_and_b32_e32 v159, 0xffff0000, v205
	v_pk_fma_f32 v[84:85], v[84:85], v[160:161], v[152:153]
	v_pk_fma_f32 v[86:87], v[86:87], v[162:163], v[154:155]
	v_pk_fma_f32 v[80:81], v[80:81], v[164:165], v[156:157]
	v_pk_fma_f32 v[82:83], v[82:83], v[166:167], v[158:159]
	s_add_u32 s14, s76, 0x90000
	s_addc_u32 s15, s77, 0
	global_store_dwordx4 v147, v[84:87], s[14:15] offset:0
	global_store_dwordx4 v147, v[80:83], s[14:15] offset:16
	s_add_u32 s14, s6, 0x48000
	s_addc_u32 s15, s7, 0
	global_load_dwordx4 v[202:205], v148, s[14:15] offset:256
	s_waitcnt vmcnt(19)
	v_lshlrev_b32_e32 v152, 16, v206
	v_and_b32_e32 v153, 0xffff0000, v206
	v_lshlrev_b32_e32 v154, 16, v207
	v_and_b32_e32 v155, 0xffff0000, v207
	v_lshlrev_b32_e32 v156, 16, v208
	v_and_b32_e32 v157, 0xffff0000, v208
	v_lshlrev_b32_e32 v158, 16, v209
	v_and_b32_e32 v159, 0xffff0000, v209
	v_pk_fma_f32 v[76:77], v[76:77], v[160:161], v[152:153]
	v_pk_fma_f32 v[78:79], v[78:79], v[162:163], v[154:155]
	v_pk_fma_f32 v[72:73], v[72:73], v[164:165], v[156:157]
	v_pk_fma_f32 v[74:75], v[74:75], v[166:167], v[158:159]
	s_add_u32 s14, s76, 0xa0000
	s_addc_u32 s15, s77, 0
	global_store_dwordx4 v147, v[76:79], s[14:15] offset:0
	global_store_dwordx4 v147, v[72:75], s[14:15] offset:16
	s_add_u32 s14, s6, 0x50000
	s_addc_u32 s15, s7, 0
	global_load_dwordx4 v[206:209], v148, s[14:15] offset:256
	s_waitcnt vmcnt(21)
	v_lshlrev_b32_e32 v152, 16, v210
	v_and_b32_e32 v153, 0xffff0000, v210
	v_lshlrev_b32_e32 v154, 16, v211
	v_and_b32_e32 v155, 0xffff0000, v211
	v_lshlrev_b32_e32 v156, 16, v212
	v_and_b32_e32 v157, 0xffff0000, v212
	v_lshlrev_b32_e32 v158, 16, v213
	v_and_b32_e32 v159, 0xffff0000, v213
	v_pk_fma_f32 v[68:69], v[68:69], v[160:161], v[152:153]
	v_pk_fma_f32 v[70:71], v[70:71], v[162:163], v[154:155]
	v_pk_fma_f32 v[64:65], v[64:65], v[164:165], v[156:157]
	v_pk_fma_f32 v[66:67], v[66:67], v[166:167], v[158:159]
	s_add_u32 s14, s76, 0xb0000
	s_addc_u32 s15, s77, 0
	global_store_dwordx4 v147, v[68:71], s[14:15] offset:0
	global_store_dwordx4 v147, v[64:67], s[14:15] offset:16
	s_add_u32 s14, s6, 0x58000
	s_addc_u32 s15, s7, 0
	global_load_dwordx4 v[210:213], v148, s[14:15] offset:256
	s_waitcnt vmcnt(21)
	v_pk_mul_f32 v[174:175], v[174:175], 0.5 op_sel_hi:[1,0]
	v_pk_mul_f32 v[176:177], v[176:177], 0.5 op_sel_hi:[1,0]
	v_pk_mul_f32 v[178:179], v[178:179], 0.5 op_sel_hi:[1,0]
	v_pk_mul_f32 v[180:181], v[180:181], 0.5 op_sel_hi:[1,0]
	v_lshlrev_b32_e32 v152, 16, v182
	v_and_b32_e32 v153, 0xffff0000, v182
	v_lshlrev_b32_e32 v154, 16, v183
	v_and_b32_e32 v155, 0xffff0000, v183
	v_lshlrev_b32_e32 v156, 16, v184
	v_and_b32_e32 v157, 0xffff0000, v184
	v_lshlrev_b32_e32 v158, 16, v185
	v_and_b32_e32 v159, 0xffff0000, v185
	v_pk_fma_f32 v[60:61], v[60:61], v[174:175], v[152:153]
	v_pk_fma_f32 v[62:63], v[62:63], v[176:177], v[154:155]
	v_pk_fma_f32 v[56:57], v[56:57], v[178:179], v[156:157]
	v_pk_fma_f32 v[58:59], v[58:59], v[180:181], v[158:159]
	s_add_u32 s14, s76, 0x0
	s_addc_u32 s15, s77, 0
	global_store_dwordx4 v147, v[60:63], s[14:15] offset:512
	global_store_dwordx4 v147, v[56:59], s[14:15] offset:528
	s_waitcnt vmcnt(20)
	v_lshlrev_b32_e32 v152, 16, v186
	v_and_b32_e32 v153, 0xffff0000, v186
	v_lshlrev_b32_e32 v154, 16, v187
	v_and_b32_e32 v155, 0xffff0000, v187
	v_lshlrev_b32_e32 v156, 16, v188
	v_and_b32_e32 v157, 0xffff0000, v188
	v_lshlrev_b32_e32 v158, 16, v189
	v_and_b32_e32 v159, 0xffff0000, v189
	v_pk_fma_f32 v[52:53], v[52:53], v[174:175], v[152:153]
	v_pk_fma_f32 v[54:55], v[54:55], v[176:177], v[154:155]
	v_pk_fma_f32 v[48:49], v[48:49], v[178:179], v[156:157]
	v_pk_fma_f32 v[50:51], v[50:51], v[180:181], v[158:159]
	s_add_u32 s14, s76, 0x10000
	s_addc_u32 s15, s77, 0
	global_store_dwordx4 v147, v[52:55], s[14:15] offset:512
	global_store_dwordx4 v147, v[48:51], s[14:15] offset:528
	s_waitcnt vmcnt(19)
	v_lshlrev_b32_e32 v152, 16, v190
	v_and_b32_e32 v153, 0xffff0000, v190
	v_lshlrev_b32_e32 v154, 16, v191
	v_and_b32_e32 v155, 0xffff0000, v191
	v_lshlrev_b32_e32 v156, 16, v192
	v_and_b32_e32 v157, 0xffff0000, v192
	v_lshlrev_b32_e32 v158, 16, v193
	v_and_b32_e32 v159, 0xffff0000, v193
	v_pk_fma_f32 v[44:45], v[44:45], v[174:175], v[152:153]
	v_pk_fma_f32 v[46:47], v[46:47], v[176:177], v[154:155]
	v_pk_fma_f32 v[40:41], v[40:41], v[178:179], v[156:157]
	v_pk_fma_f32 v[42:43], v[42:43], v[180:181], v[158:159]
	s_add_u32 s14, s76, 0x20000
	s_addc_u32 s15, s77, 0
	global_store_dwordx4 v147, v[44:47], s[14:15] offset:512
	global_store_dwordx4 v147, v[40:43], s[14:15] offset:528
	s_waitcnt vmcnt(18)
	v_lshlrev_b32_e32 v152, 16, v194
	v_and_b32_e32 v153, 0xffff0000, v194
	v_lshlrev_b32_e32 v154, 16, v195
	v_and_b32_e32 v155, 0xffff0000, v195
	v_lshlrev_b32_e32 v156, 16, v196
	v_and_b32_e32 v157, 0xffff0000, v196
	v_lshlrev_b32_e32 v158, 16, v197
	v_and_b32_e32 v159, 0xffff0000, v197
	v_pk_fma_f32 v[36:37], v[36:37], v[174:175], v[152:153]
	v_pk_fma_f32 v[38:39], v[38:39], v[176:177], v[154:155]
	v_pk_fma_f32 v[32:33], v[32:33], v[178:179], v[156:157]
	v_pk_fma_f32 v[34:35], v[34:35], v[180:181], v[158:159]
	s_add_u32 s14, s76, 0x30000
	s_addc_u32 s15, s77, 0
	global_store_dwordx4 v147, v[36:39], s[14:15] offset:512
	global_store_dwordx4 v147, v[32:35], s[14:15] offset:528
	s_waitcnt vmcnt(17)
	v_lshlrev_b32_e32 v152, 16, v198
	v_and_b32_e32 v153, 0xffff0000, v198
	v_lshlrev_b32_e32 v154, 16, v199
	v_and_b32_e32 v155, 0xffff0000, v199
	v_lshlrev_b32_e32 v156, 16, v200
	v_and_b32_e32 v157, 0xffff0000, v200
	v_lshlrev_b32_e32 v158, 16, v201
	v_and_b32_e32 v159, 0xffff0000, v201
	v_pk_fma_f32 v[28:29], v[28:29], v[174:175], v[152:153]
	v_pk_fma_f32 v[30:31], v[30:31], v[176:177], v[154:155]
	v_pk_fma_f32 v[24:25], v[24:25], v[178:179], v[156:157]
	v_pk_fma_f32 v[26:27], v[26:27], v[180:181], v[158:159]
	s_add_u32 s14, s76, 0x80000
	s_addc_u32 s15, s77, 0
	global_store_dwordx4 v147, v[28:31], s[14:15] offset:512
	global_store_dwordx4 v147, v[24:27], s[14:15] offset:528
	s_waitcnt vmcnt(16)
	v_lshlrev_b32_e32 v152, 16, v202
	v_and_b32_e32 v153, 0xffff0000, v202
	v_lshlrev_b32_e32 v154, 16, v203
	v_and_b32_e32 v155, 0xffff0000, v203
	v_lshlrev_b32_e32 v156, 16, v204
	v_and_b32_e32 v157, 0xffff0000, v204
	v_lshlrev_b32_e32 v158, 16, v205
	v_and_b32_e32 v159, 0xffff0000, v205
	v_pk_fma_f32 v[20:21], v[20:21], v[174:175], v[152:153]
	v_pk_fma_f32 v[22:23], v[22:23], v[176:177], v[154:155]
	v_pk_fma_f32 v[16:17], v[16:17], v[178:179], v[156:157]
	v_pk_fma_f32 v[18:19], v[18:19], v[180:181], v[158:159]
	s_add_u32 s14, s76, 0x90000
	s_addc_u32 s15, s77, 0
	global_store_dwordx4 v147, v[20:23], s[14:15] offset:512
	global_store_dwordx4 v147, v[16:19], s[14:15] offset:528
	s_waitcnt vmcnt(15)
	v_lshlrev_b32_e32 v152, 16, v206
	v_and_b32_e32 v153, 0xffff0000, v206
	v_lshlrev_b32_e32 v154, 16, v207
	v_and_b32_e32 v155, 0xffff0000, v207
	v_lshlrev_b32_e32 v156, 16, v208
	v_and_b32_e32 v157, 0xffff0000, v208
	v_lshlrev_b32_e32 v158, 16, v209
	v_and_b32_e32 v159, 0xffff0000, v209
	v_pk_fma_f32 v[12:13], v[12:13], v[174:175], v[152:153]
	v_pk_fma_f32 v[14:15], v[14:15], v[176:177], v[154:155]
	v_pk_fma_f32 v[8:9], v[8:9], v[178:179], v[156:157]
	v_pk_fma_f32 v[10:11], v[10:11], v[180:181], v[158:159]
	s_add_u32 s14, s76, 0xa0000
	s_addc_u32 s15, s77, 0
	global_store_dwordx4 v147, v[12:15], s[14:15] offset:512
	global_store_dwordx4 v147, v[8:11], s[14:15] offset:528
	s_waitcnt vmcnt(14)
	v_lshlrev_b32_e32 v152, 16, v210
	v_and_b32_e32 v153, 0xffff0000, v210
	v_lshlrev_b32_e32 v154, 16, v211
	v_and_b32_e32 v155, 0xffff0000, v211
	v_lshlrev_b32_e32 v156, 16, v212
	v_and_b32_e32 v157, 0xffff0000, v212
	v_lshlrev_b32_e32 v158, 16, v213
	v_and_b32_e32 v159, 0xffff0000, v213
	v_pk_fma_f32 v[4:5], v[4:5], v[174:175], v[152:153]
	v_pk_fma_f32 v[6:7], v[6:7], v[176:177], v[154:155]
	v_pk_fma_f32 v[0:1], v[0:1], v[178:179], v[156:157]
	v_pk_fma_f32 v[2:3], v[2:3], v[180:181], v[158:159]
	s_add_u32 s14, s76, 0xb0000
	s_addc_u32 s15, s77, 0
	global_store_dwordx4 v147, v[4:7], s[14:15] offset:512
	global_store_dwordx4 v147, v[0:3], s[14:15] offset:528
	s_and_b64 vcc, exec, s[0:1]
	s_mov_b64 s[0:1], -1
	s_cbranch_vccnz .LBB0_990
	s_andn2_b64 vcc, exec, s[4:5]
	s_cbranch_vccnz .LBB0_989
	s_barrier
	s_branch .LBB0_989
